# v39: v33 with the second-half residual-load wait moved ahead of the conditional row-ssq atomics in EpiRes (phases 2,7,9)
# baseline (speedup 1.0000x reference)
.LBB0_265:
	s_mov_b32 s98, 0x40000
	s_mov_b32 s99, 0
	v_and_b32_e32 v121, 64, v230
	v_xor_b32_e32 v120, 16, v230
	v_add_u32_e32 v121, 64, v121
	v_cmp_lt_i32_e32 vcc, v120, v121
	s_lshl_b32 s42, s75, 8
	s_lshl_b32 s34, s15, 8
	v_cndmask_b32_e32 v120, v230, v120, vcc
	v_add_u32_e32 v156, s42, v225
	s_ashr_i32 s35, s34, 31
	v_lshlrev_b32_e32 v167, 2, v120
	v_xor_b32_e32 v120, 32, v230
	v_cmp_lt_i32_e32 vcc, v120, v121
	s_lshl_b64 s[34:35], s[34:35], 1
	v_ashrrev_i32_e32 v157, 31, v156
	v_cndmask_b32_e32 v120, v230, v120, vcc
	v_lshl_add_u64 v[158:159], v[204:205], 0, s[34:35]
	v_lshlrev_b64 v[172:173], 11, v[156:157]
	v_lshlrev_b32_e32 v166, 2, v120
	v_lshl_add_u64 v[120:121], v[158:159], 0, v[172:173]
	v_lshl_add_u64 v[190:191], v[120:121], 0, s[98:99]
	global_load_dwordx4 v[168:171], v[120:121], off
	global_load_dwordx4 v[152:155], v[120:121], off offset:256
	global_load_dwordx4 v[182:185], v[190:191], off
	global_load_dwordx4 v[186:189], v[190:191], off offset:256
	v_or_b32_e32 v120, 16, v156
	v_ashrrev_i32_e32 v121, 31, v120
	v_lshlrev_b64 v[164:165], 11, v[120:121]
	v_lshl_add_u64 v[120:121], v[158:159], 0, v[164:165]
	v_lshl_add_u64 v[190:191], v[120:121], 0, s[98:99]
	global_load_dwordx4 v[148:151], v[120:121], off
	global_load_dwordx4 v[144:147], v[120:121], off offset:256
	global_load_dwordx4 v[216:219], v[190:191], off
	global_load_dwordx4 v[220:223], v[190:191], off offset:256
	v_or_b32_e32 v120, 32, v156
	v_ashrrev_i32_e32 v121, 31, v120
	v_lshlrev_b64 v[162:163], 11, v[120:121]
	v_lshl_add_u64 v[120:121], v[158:159], 0, v[162:163]
	v_lshl_add_u64 v[190:191], v[120:121], 0, s[98:99]
	global_load_dwordx4 v[140:143], v[120:121], off
	global_load_dwordx4 v[136:139], v[120:121], off offset:256
	global_load_dwordx4 v[236:239], v[190:191], off
	global_load_dwordx4 v[240:243], v[190:191], off offset:256
	v_or_b32_e32 v120, 48, v156
	v_ashrrev_i32_e32 v121, 31, v120
	v_lshlrev_b64 v[160:161], 11, v[120:121]
	v_lshl_add_u64 v[120:121], v[158:159], 0, v[160:161]
	v_lshl_add_u64 v[190:191], v[120:121], 0, s[98:99]
	global_load_dwordx4 v[132:135], v[120:121], off
	s_nop 0
	global_load_dwordx4 v[120:123], v[120:121], off offset:256
	global_load_dwordx4 v[246:249], v[190:191], off
	global_load_dwordx4 v[250:253], v[190:191], off offset:256
	s_mov_b32 s15, s1
	s_ashr_i32 s43, s42, 31
	s_waitcnt vmcnt(14)
	v_lshlrev_b32_e32 v174, 16, v168
	v_and_b32_e32 v175, 0xffff0000, v168
	v_lshlrev_b32_e32 v168, 16, v169
	v_and_b32_e32 v169, 0xffff0000, v169
	v_pk_fma_f32 v[130:131], v[130:131], 0.5, v[168:169] op_sel_hi:[1,0,1]
	v_pk_fma_f32 v[168:169], v[128:129], 0.5, v[174:175] op_sel_hi:[1,0,1]
	v_cvt_pk_bf16_f32 v129, v130, v131
	v_mul_f32_e32 v157, v169, v169
	v_mul_f32_e32 v131, v131, v131
	v_fmac_f32_e32 v157, v168, v168
	v_fmac_f32_e32 v131, v130, v130
	v_add_f32_e32 v157, v157, v131
	v_lshlrev_b32_e32 v130, 16, v170
	v_and_b32_e32 v131, 0xffff0000, v170
	v_cvt_pk_bf16_f32 v128, v168, v169
	v_lshlrev_b32_e32 v168, 16, v171
	v_and_b32_e32 v169, 0xffff0000, v171
	v_pk_fma_f32 v[124:125], v[124:125], 0.5, v[130:131] op_sel_hi:[1,0,1]
	v_pk_fma_f32 v[126:127], v[126:127], 0.5, v[168:169] op_sel_hi:[1,0,1]
	v_cvt_pk_bf16_f32 v130, v124, v125
	v_mul_f32_e32 v125, v125, v125
	v_fmac_f32_e32 v125, v124, v124
	v_mul_f32_e32 v124, v127, v127
	v_fmac_f32_e32 v124, v126, v126
	v_add_f32_e32 v124, v125, v124
	v_add_f32_e32 v157, v157, v124
	v_lshl_add_u64 v[124:125], s[78:79], 0, v[172:173]
	v_lshl_add_u64 v[124:125], v[124:125], 0, s[34:35]
	v_lshl_add_u64 v[124:125], v[124:125], 0, s[14:15]
	v_cvt_pk_bf16_f32 v131, v126, v127
	v_lshl_add_u64 v[124:125], v[124:125], 0, v[200:201]
	global_store_dwordx4 v[124:125], v[128:131], off
	v_lshlrev_b32_e32 v126, 16, v152
	v_and_b32_e32 v127, 0xffff0000, v152
	v_lshlrev_b32_e32 v128, 16, v153
	v_and_b32_e32 v129, 0xffff0000, v153
	v_pk_fma_f32 v[118:119], v[118:119], 0.5, v[128:129] op_sel_hi:[1,0,1]
	v_pk_fma_f32 v[126:127], v[116:117], 0.5, v[126:127] op_sel_hi:[1,0,1]
	v_cvt_pk_bf16_f32 v117, v118, v119
	v_cvt_pk_bf16_f32 v116, v126, v127
	v_mul_f32_e32 v127, v127, v127
	v_mul_f32_e32 v119, v119, v119
	v_fmac_f32_e32 v127, v126, v126
	v_fmac_f32_e32 v119, v118, v118
	v_add_f32_e32 v118, v127, v119
	v_add_f32_e32 v128, v157, v118
	v_lshlrev_b32_e32 v118, 16, v154
	v_and_b32_e32 v119, 0xffff0000, v154
	v_lshlrev_b32_e32 v126, 16, v155
	v_and_b32_e32 v127, 0xffff0000, v155
	v_pk_fma_f32 v[112:113], v[112:113], 0.5, v[118:119] op_sel_hi:[1,0,1]
	v_pk_fma_f32 v[114:115], v[114:115], 0.5, v[126:127] op_sel_hi:[1,0,1]
	v_cvt_pk_bf16_f32 v118, v112, v113
	v_mul_f32_e32 v113, v113, v113
	v_cvt_pk_bf16_f32 v119, v114, v115
	v_fmac_f32_e32 v113, v112, v112
	v_mul_f32_e32 v112, v115, v115
	v_fmac_f32_e32 v112, v114, v114
	global_store_dwordx4 v[124:125], v[116:119], off offset:256
	s_waitcnt vmcnt(12)
	v_lshlrev_b32_e32 v114, 16, v148
	v_and_b32_e32 v115, 0xffff0000, v148
	v_lshlrev_b32_e32 v116, 16, v149
	v_and_b32_e32 v117, 0xffff0000, v149
	v_pk_fma_f32 v[110:111], v[110:111], 0.5, v[116:117] op_sel_hi:[1,0,1]
	v_pk_fma_f32 v[114:115], v[108:109], 0.5, v[114:115] op_sel_hi:[1,0,1]
	v_cvt_pk_bf16_f32 v109, v110, v111
	v_cvt_pk_bf16_f32 v108, v114, v115
	v_mul_f32_e32 v115, v115, v115
	v_mul_f32_e32 v111, v111, v111
	v_fmac_f32_e32 v115, v114, v114
	v_fmac_f32_e32 v111, v110, v110
	v_add_f32_e32 v116, v115, v111
	v_lshlrev_b32_e32 v110, 16, v150
	v_and_b32_e32 v111, 0xffff0000, v150
	v_lshlrev_b32_e32 v114, 16, v151
	v_and_b32_e32 v115, 0xffff0000, v151
	v_pk_fma_f32 v[104:105], v[104:105], 0.5, v[110:111] op_sel_hi:[1,0,1]
	v_pk_fma_f32 v[106:107], v[106:107], 0.5, v[114:115] op_sel_hi:[1,0,1]
	v_cvt_pk_bf16_f32 v110, v104, v105
	v_mul_f32_e32 v105, v105, v105
	v_fmac_f32_e32 v105, v104, v104
	v_mul_f32_e32 v104, v107, v107
	v_fmac_f32_e32 v104, v106, v106
	v_add_f32_e32 v104, v105, v104
	v_add_f32_e32 v114, v116, v104
	v_lshl_add_u64 v[104:105], s[78:79], 0, v[164:165]
	v_lshl_add_u64 v[104:105], v[104:105], 0, s[34:35]
	v_lshl_add_u64 v[104:105], v[104:105], 0, s[14:15]
	v_cvt_pk_bf16_f32 v111, v106, v107
	v_lshl_add_u64 v[104:105], v[104:105], 0, v[200:201]
	global_store_dwordx4 v[104:105], v[108:111], off
	v_lshlrev_b32_e32 v106, 16, v144
	v_and_b32_e32 v107, 0xffff0000, v144
	v_lshlrev_b32_e32 v108, 16, v145
	v_and_b32_e32 v109, 0xffff0000, v145
	v_pk_fma_f32 v[102:103], v[102:103], 0.5, v[108:109] op_sel_hi:[1,0,1]
	v_pk_fma_f32 v[106:107], v[100:101], 0.5, v[106:107] op_sel_hi:[1,0,1]
	v_cvt_pk_bf16_f32 v101, v102, v103
	v_cvt_pk_bf16_f32 v100, v106, v107
	v_mul_f32_e32 v107, v107, v107
	v_mul_f32_e32 v103, v103, v103
	v_fmac_f32_e32 v107, v106, v106
	v_fmac_f32_e32 v103, v102, v102
	v_add_f32_e32 v102, v107, v103
	v_add_f32_e32 v108, v114, v102
	v_lshlrev_b32_e32 v102, 16, v146
	v_and_b32_e32 v103, 0xffff0000, v146
	v_lshlrev_b32_e32 v106, 16, v147
	v_and_b32_e32 v107, 0xffff0000, v147
	v_pk_fma_f32 v[96:97], v[96:97], 0.5, v[102:103] op_sel_hi:[1,0,1]
	v_pk_fma_f32 v[98:99], v[98:99], 0.5, v[106:107] op_sel_hi:[1,0,1]
	v_cvt_pk_bf16_f32 v102, v96, v97
	v_mul_f32_e32 v97, v97, v97
	v_cvt_pk_bf16_f32 v103, v98, v99
	v_fmac_f32_e32 v97, v96, v96
	v_mul_f32_e32 v96, v99, v99
	v_fmac_f32_e32 v96, v98, v98
	global_store_dwordx4 v[104:105], v[100:103], off offset:256
	s_waitcnt vmcnt(10)
	v_lshlrev_b32_e32 v98, 16, v140
	v_and_b32_e32 v99, 0xffff0000, v140
	v_lshlrev_b32_e32 v100, 16, v141
	v_and_b32_e32 v101, 0xffff0000, v141
	v_pk_fma_f32 v[94:95], v[94:95], 0.5, v[100:101] op_sel_hi:[1,0,1]
	v_pk_fma_f32 v[98:99], v[92:93], 0.5, v[98:99] op_sel_hi:[1,0,1]
	v_cvt_pk_bf16_f32 v93, v94, v95
	v_cvt_pk_bf16_f32 v92, v98, v99
	v_mul_f32_e32 v99, v99, v99
	v_mul_f32_e32 v95, v95, v95
	v_fmac_f32_e32 v99, v98, v98
	v_fmac_f32_e32 v95, v94, v94
	v_add_f32_e32 v100, v99, v95
	v_lshlrev_b32_e32 v94, 16, v142
	v_and_b32_e32 v95, 0xffff0000, v142
	v_lshlrev_b32_e32 v98, 16, v143
	v_and_b32_e32 v99, 0xffff0000, v143
	v_pk_fma_f32 v[88:89], v[88:89], 0.5, v[94:95] op_sel_hi:[1,0,1]
	v_pk_fma_f32 v[90:91], v[90:91], 0.5, v[98:99] op_sel_hi:[1,0,1]
	v_cvt_pk_bf16_f32 v94, v88, v89
	v_mul_f32_e32 v89, v89, v89
	v_fmac_f32_e32 v89, v88, v88
	v_mul_f32_e32 v88, v91, v91
	v_fmac_f32_e32 v88, v90, v90
	v_add_f32_e32 v88, v89, v88
	v_add_f32_e32 v98, v100, v88
	v_lshl_add_u64 v[88:89], s[78:79], 0, v[162:163]
	v_lshl_add_u64 v[88:89], v[88:89], 0, s[34:35]
	v_lshl_add_u64 v[88:89], v[88:89], 0, s[14:15]
	v_cvt_pk_bf16_f32 v95, v90, v91
	v_lshl_add_u64 v[88:89], v[88:89], 0, v[200:201]
	global_store_dwordx4 v[88:89], v[92:95], off
	v_lshlrev_b32_e32 v90, 16, v136
	v_and_b32_e32 v91, 0xffff0000, v136
	v_lshlrev_b32_e32 v92, 16, v137
	v_and_b32_e32 v93, 0xffff0000, v137
	v_pk_fma_f32 v[86:87], v[86:87], 0.5, v[92:93] op_sel_hi:[1,0,1]
	v_pk_fma_f32 v[90:91], v[84:85], 0.5, v[90:91] op_sel_hi:[1,0,1]
	v_cvt_pk_bf16_f32 v85, v86, v87
	v_cvt_pk_bf16_f32 v84, v90, v91
	v_mul_f32_e32 v91, v91, v91
	v_mul_f32_e32 v87, v87, v87
	v_fmac_f32_e32 v91, v90, v90
	v_fmac_f32_e32 v87, v86, v86
	v_add_f32_e32 v86, v91, v87
	v_add_f32_e32 v92, v98, v86
	v_lshlrev_b32_e32 v86, 16, v138
	v_and_b32_e32 v87, 0xffff0000, v138
	v_lshlrev_b32_e32 v90, 16, v139
	v_and_b32_e32 v91, 0xffff0000, v139
	v_pk_fma_f32 v[80:81], v[80:81], 0.5, v[86:87] op_sel_hi:[1,0,1]
	v_pk_fma_f32 v[82:83], v[82:83], 0.5, v[90:91] op_sel_hi:[1,0,1]
	v_cvt_pk_bf16_f32 v86, v80, v81
	v_mul_f32_e32 v81, v81, v81
	v_cvt_pk_bf16_f32 v87, v82, v83
	v_fmac_f32_e32 v81, v80, v80
	v_mul_f32_e32 v80, v83, v83
	v_fmac_f32_e32 v80, v82, v82
	global_store_dwordx4 v[88:89], v[84:87], off offset:256
	s_waitcnt vmcnt(8)
	v_lshlrev_b32_e32 v82, 16, v132
	v_and_b32_e32 v83, 0xffff0000, v132
	v_lshlrev_b32_e32 v84, 16, v133
	v_and_b32_e32 v85, 0xffff0000, v133
	v_pk_fma_f32 v[78:79], v[78:79], 0.5, v[84:85] op_sel_hi:[1,0,1]
	v_pk_fma_f32 v[82:83], v[76:77], 0.5, v[82:83] op_sel_hi:[1,0,1]
	v_cvt_pk_bf16_f32 v77, v78, v79
	v_cvt_pk_bf16_f32 v76, v82, v83
	v_mul_f32_e32 v83, v83, v83
	v_mul_f32_e32 v79, v79, v79
	v_fmac_f32_e32 v83, v82, v82
	v_fmac_f32_e32 v79, v78, v78
	v_add_f32_e32 v84, v83, v79
	v_lshlrev_b32_e32 v78, 16, v134
	v_and_b32_e32 v79, 0xffff0000, v134
	v_lshlrev_b32_e32 v82, 16, v135
	v_and_b32_e32 v83, 0xffff0000, v135
	v_pk_fma_f32 v[72:73], v[72:73], 0.5, v[78:79] op_sel_hi:[1,0,1]
	v_pk_fma_f32 v[74:75], v[74:75], 0.5, v[82:83] op_sel_hi:[1,0,1]
	v_cvt_pk_bf16_f32 v78, v72, v73
	v_mul_f32_e32 v73, v73, v73
	v_fmac_f32_e32 v73, v72, v72
	v_mul_f32_e32 v72, v75, v75
	v_fmac_f32_e32 v72, v74, v74
	v_add_f32_e32 v72, v73, v72
	v_add_f32_e32 v82, v84, v72
	v_lshl_add_u64 v[72:73], s[78:79], 0, v[160:161]
	v_lshl_add_u64 v[72:73], v[72:73], 0, s[34:35]
	v_lshl_add_u64 v[72:73], v[72:73], 0, s[14:15]
	v_cvt_pk_bf16_f32 v79, v74, v75
	v_lshl_add_u64 v[72:73], v[72:73], 0, v[200:201]
	global_store_dwordx4 v[72:73], v[76:79], off
	v_lshlrev_b32_e32 v74, 16, v120
	v_and_b32_e32 v75, 0xffff0000, v120
	v_lshlrev_b32_e32 v76, 16, v121
	v_and_b32_e32 v77, 0xffff0000, v121
	v_pk_fma_f32 v[70:71], v[70:71], 0.5, v[76:77] op_sel_hi:[1,0,1]
	v_pk_fma_f32 v[74:75], v[68:69], 0.5, v[74:75] op_sel_hi:[1,0,1]
	v_cvt_pk_bf16_f32 v69, v70, v71
	v_cvt_pk_bf16_f32 v68, v74, v75
	v_mul_f32_e32 v75, v75, v75
	v_mul_f32_e32 v71, v71, v71
	v_fmac_f32_e32 v75, v74, v74
	v_fmac_f32_e32 v71, v70, v70
	v_add_f32_e32 v70, v75, v71
	v_add_f32_e32 v76, v82, v70
	v_lshlrev_b32_e32 v70, 16, v122
	v_and_b32_e32 v71, 0xffff0000, v122
	v_lshlrev_b32_e32 v74, 16, v123
	v_and_b32_e32 v75, 0xffff0000, v123
	v_pk_fma_f32 v[64:65], v[64:65], 0.5, v[70:71] op_sel_hi:[1,0,1]
	v_pk_fma_f32 v[66:67], v[66:67], 0.5, v[74:75] op_sel_hi:[1,0,1]
	v_cvt_pk_bf16_f32 v70, v64, v65
	v_mul_f32_e32 v65, v65, v65
	v_fmac_f32_e32 v65, v64, v64
	v_mul_f32_e32 v64, v67, v67
	v_fmac_f32_e32 v64, v66, v66
	v_add_f32_e32 v112, v113, v112
	v_add_f32_e32 v96, v97, v96
	v_add_f32_e32 v80, v81, v80
	v_add_f32_e32 v64, v65, v64
	v_add_f32_e32 v112, v112, v128
	v_add_f32_e32 v96, v96, v108
	v_add_f32_e32 v80, v80, v92
	v_add_f32_e32 v64, v64, v76
	ds_bpermute_b32 v113, v167, v112
	ds_bpermute_b32 v97, v167, v96
	ds_bpermute_b32 v81, v167, v80
	ds_bpermute_b32 v65, v167, v64
	v_cvt_pk_bf16_f32 v71, v66, v67
	s_waitcnt lgkmcnt(3)
	v_add_f32_e32 v112, v112, v113
	s_waitcnt lgkmcnt(2)
	v_add_f32_e32 v96, v96, v97
	s_waitcnt lgkmcnt(1)
	v_add_f32_e32 v80, v80, v81
	s_waitcnt lgkmcnt(0)
	v_add_f32_e32 v64, v64, v65
	ds_bpermute_b32 v113, v166, v112
	ds_bpermute_b32 v97, v166, v96
	ds_bpermute_b32 v81, v166, v80
	ds_bpermute_b32 v65, v166, v64
	v_lshl_add_u64 v[92:93], s[42:43], 2, v[206:207]
	global_store_dwordx4 v[72:73], v[68:71], off offset:256
	s_waitcnt vmcnt(8)
	s_and_saveexec_b64 s[42:43], s[2:3]
	v_readlane_b32 s92, v245, 60
	v_readlane_b32 s93, v245, 61
	v_readlane_b32 s94, v245, 62
	v_readlane_b32 s95, v245, 63
	v_readlane_b32 s97, v244, 0
	s_cbranch_execz .LBB0_267
	s_waitcnt lgkmcnt(3)
	v_add_f32_e32 v67, v112, v113
	s_waitcnt lgkmcnt(0)
	v_add_f32_e32 v64, v64, v65
	v_add_f32_e32 v65, v80, v81
	v_add_f32_e32 v66, v96, v97
	global_atomic_add_f32 v[92:93], v67, off
	global_atomic_add_f32 v[92:93], v66, off offset:64
	global_atomic_add_f32 v[92:93], v65, off offset:128
	global_atomic_add_f32 v[92:93], v64, off offset:192

.LBB0_1555:
	s_mov_b32 s98, 0x40000
	s_mov_b32 s99, 0
	s_lshl_b32 s20, s18, 8
	s_lshl_b32 s18, s19, 8
	v_add_u32_e32 v162, s20, v170
	s_ashr_i32 s19, s18, 31
	s_lshl_b64 s[18:19], s[18:19], 1
	v_ashrrev_i32_e32 v163, 31, v162
	v_lshl_add_u64 v[164:165], v[150:151], 0, s[18:19]
	v_lshlrev_b64 v[128:129], 11, v[162:163]
	v_lshl_add_u64 v[130:131], v[164:165], 0, v[128:129]
	v_lshl_add_u64 v[222:223], v[130:131], 0, s[98:99]
	global_load_dwordx4 v[178:181], v[130:131], off
	global_load_dwordx4 v[182:185], v[130:131], off offset:256
	global_load_dwordx4 v[210:213], v[222:223], off
	global_load_dwordx4 v[214:217], v[222:223], off offset:256
	v_and_b32_e32 v131, 64, v175
	v_xor_b32_e32 v130, 16, v175
	v_add_u32_e32 v131, 64, v131
	v_cmp_lt_i32_e32 vcc, v130, v131
	v_xor_b32_e32 v132, 32, v175
	v_or_b32_e32 v134, 48, v162
	v_cndmask_b32_e32 v133, v175, v130, vcc
	v_or_b32_e32 v130, 16, v162
	v_cmp_lt_i32_e32 vcc, v132, v131
	v_ashrrev_i32_e32 v131, 31, v130
	v_lshlrev_b64 v[198:199], 11, v[130:131]
	v_lshl_add_u64 v[130:131], v[164:165], 0, v[198:199]
	v_lshl_add_u64 v[222:223], v[130:131], 0, s[98:99]
	global_load_dwordx4 v[186:189], v[130:131], off
	v_cndmask_b32_e32 v135, v175, v132, vcc
	v_or_b32_e32 v132, 32, v162
	v_lshlrev_b32_e32 v176, 2, v133
	v_ashrrev_i32_e32 v133, 31, v132
	v_lshlrev_b32_e32 v163, 2, v135
	v_ashrrev_i32_e32 v135, 31, v134
	v_lshlrev_b64 v[168:169], 11, v[132:133]
	v_lshlrev_b64 v[166:167], 11, v[134:135]
	v_lshl_add_u64 v[128:129], s[78:79], 0, v[128:129]
	v_lshl_add_u64 v[132:133], v[164:165], 0, v[168:169]
	v_lshl_add_u64 v[200:201], v[164:165], 0, v[166:167]
	v_lshl_add_u64 v[202:203], v[128:129], 0, s[18:19]
	global_load_dwordx4 v[190:193], v[130:131], off offset:256
	global_load_dwordx4 v[218:221], v[222:223], off
	global_load_dwordx4 v[226:229], v[222:223], off offset:256
	v_lshl_add_u64 v[222:223], v[132:133], 0, s[98:99]
	global_load_dwordx4 v[194:197], v[132:133], off
	global_load_dwordx4 v[136:139], v[132:133], off offset:256
	global_load_dwordx4 v[236:239], v[222:223], off
	global_load_dwordx4 v[240:243], v[222:223], off offset:256
	s_nop 0
	v_lshl_add_u64 v[222:223], v[200:201], 0, s[98:99]
	global_load_dwordx4 v[132:135], v[200:201], off
	global_load_dwordx4 v[128:131], v[200:201], off offset:256
	global_load_dwordx4 v[246:249], v[222:223], off
	global_load_dwordx4 v[250:253], v[222:223], off offset:256
	v_lshl_add_u64 v[200:201], v[202:203], 0, s[0:1]
	v_lshl_add_u64 v[200:201], v[200:201], 0, v[148:149]
	s_ashr_i32 s21, s20, 31
	s_waitcnt vmcnt(14)
	v_lshlrev_b32_e32 v202, 16, v178
	v_and_b32_e32 v203, 0xffff0000, v178
	v_lshlrev_b32_e32 v178, 16, v179
	v_and_b32_e32 v179, 0xffff0000, v179
	v_lshlrev_b32_e32 v204, 16, v180
	v_and_b32_e32 v205, 0xffff0000, v180
	v_lshlrev_b32_e32 v180, 16, v181
	v_and_b32_e32 v181, 0xffff0000, v181
	v_lshlrev_b32_e32 v206, 16, v182
	v_and_b32_e32 v207, 0xffff0000, v182
	v_lshlrev_b32_e32 v182, 16, v183
	v_and_b32_e32 v183, 0xffff0000, v183
	v_lshlrev_b32_e32 v208, 16, v184
	v_and_b32_e32 v209, 0xffff0000, v184
	v_lshlrev_b32_e32 v184, 16, v185
	v_and_b32_e32 v185, 0xffff0000, v185
	v_pk_add_f32 v[126:127], v[126:127], v[178:179]
	v_pk_add_f32 v[124:125], v[124:125], v[202:203]
	v_pk_add_f32 v[122:123], v[122:123], v[180:181]
	v_pk_add_f32 v[120:121], v[120:121], v[204:205]
	v_pk_add_f32 v[118:119], v[118:119], v[182:183]
	v_pk_add_f32 v[178:179], v[116:117], v[206:207]
	v_pk_add_f32 v[180:181], v[114:115], v[184:185]
	v_pk_add_f32 v[182:183], v[112:113], v[208:209]
	v_cvt_pk_bf16_f32 v112, v124, v125
	v_mul_f32_e32 v117, v125, v125
	v_mul_f32_e32 v125, v127, v127
	v_cvt_pk_bf16_f32 v114, v120, v121
	v_cvt_pk_bf16_f32 v115, v122, v123
	v_mul_f32_e32 v121, v121, v121
	v_mul_f32_e32 v123, v123, v123
	v_cvt_pk_bf16_f32 v113, v126, v127
	v_mul_f32_e32 v127, v179, v179
	v_mul_f32_e32 v177, v119, v119
	v_fmac_f32_e32 v117, v124, v124
	v_fmac_f32_e32 v125, v126, v126
	v_fmac_f32_e32 v121, v120, v120
	v_fmac_f32_e32 v123, v122, v122
	global_store_dwordx4 v[200:201], v[112:115], off
	v_fmac_f32_e32 v127, v178, v178
	v_fmac_f32_e32 v177, v118, v118
	v_add_f32_e32 v112, v117, v125
	v_add_f32_e32 v113, v121, v123
	v_cvt_pk_bf16_f32 v116, v178, v179
	v_add_f32_e32 v114, v127, v177
	v_add_f32_e32 v112, v112, v113
	v_cvt_pk_bf16_f32 v117, v118, v119
	v_cvt_pk_bf16_f32 v118, v182, v183
	v_cvt_pk_bf16_f32 v119, v180, v181
	v_add_f32_e32 v112, v112, v114
	global_store_dwordx4 v[200:201], v[116:119], off offset:256
	s_waitcnt vmcnt(12)
	v_lshlrev_b32_e32 v114, 16, v186
	v_and_b32_e32 v115, 0xffff0000, v186
	v_lshlrev_b32_e32 v116, 16, v187
	v_and_b32_e32 v117, 0xffff0000, v187
	v_pk_add_f32 v[110:111], v[110:111], v[116:117]
	v_pk_add_f32 v[114:115], v[108:109], v[114:115]
	v_cvt_pk_bf16_f32 v109, v110, v111
	v_cvt_pk_bf16_f32 v108, v114, v115
	v_mul_f32_e32 v115, v115, v115
	v_mul_f32_e32 v111, v111, v111
	v_fmac_f32_e32 v115, v114, v114
	v_fmac_f32_e32 v111, v110, v110
	v_add_f32_e32 v116, v115, v111
	v_lshlrev_b32_e32 v110, 16, v188
	v_and_b32_e32 v111, 0xffff0000, v188
	v_lshlrev_b32_e32 v114, 16, v189
	v_and_b32_e32 v115, 0xffff0000, v189
	v_pk_add_f32 v[104:105], v[104:105], v[110:111]
	v_pk_add_f32 v[106:107], v[106:107], v[114:115]
	v_cvt_pk_bf16_f32 v110, v104, v105
	v_mul_f32_e32 v105, v105, v105
	v_fmac_f32_e32 v105, v104, v104
	v_mul_f32_e32 v104, v107, v107
	v_fmac_f32_e32 v104, v106, v106
	v_add_f32_e32 v104, v105, v104
	v_add_f32_e32 v114, v116, v104
	v_lshl_add_u64 v[104:105], s[78:79], 0, v[198:199]
	v_lshl_add_u64 v[104:105], v[104:105], 0, s[18:19]
	v_lshl_add_u64 v[104:105], v[104:105], 0, s[0:1]
	v_cvt_pk_bf16_f32 v111, v106, v107
	v_lshl_add_u64 v[104:105], v[104:105], 0, v[148:149]
	v_lshlrev_b32_e32 v106, 16, v190
	v_and_b32_e32 v107, 0xffff0000, v190
	global_store_dwordx4 v[104:105], v[108:111], off
	v_pk_add_f32 v[106:107], v[100:101], v[106:107]
	v_mul_f32_e32 v179, v183, v183
	v_lshlrev_b32_e32 v108, 16, v191
	v_and_b32_e32 v109, 0xffff0000, v191
	v_pk_add_f32 v[102:103], v[102:103], v[108:109]
	v_mul_f32_e32 v101, v107, v107
	v_cvt_pk_bf16_f32 v100, v106, v107
	v_fmac_f32_e32 v101, v106, v106
	v_mul_f32_e32 v106, v103, v103
	v_fmac_f32_e32 v106, v102, v102
	v_add_f32_e32 v101, v101, v106
	v_lshlrev_b32_e32 v106, 16, v192
	v_and_b32_e32 v107, 0xffff0000, v192
	v_lshlrev_b32_e32 v108, 16, v193
	v_and_b32_e32 v109, 0xffff0000, v193
	v_pk_add_f32 v[98:99], v[98:99], v[108:109]
	v_pk_add_f32 v[96:97], v[96:97], v[106:107]
	v_mul_f32_e32 v107, v99, v99
	v_mul_f32_e32 v106, v97, v97
	v_fmac_f32_e32 v106, v96, v96
	v_fmac_f32_e32 v107, v98, v98
	v_add_f32_e32 v101, v114, v101
	v_add_f32_e32 v106, v106, v107
	v_add_f32_e32 v106, v106, v101
	v_cvt_pk_bf16_f32 v101, v102, v103
	v_cvt_pk_bf16_f32 v102, v96, v97
	v_cvt_pk_bf16_f32 v103, v98, v99
	global_store_dwordx4 v[104:105], v[100:103], off offset:256
	s_waitcnt vmcnt(10)
	v_lshlrev_b32_e32 v98, 16, v194
	v_and_b32_e32 v99, 0xffff0000, v194
	v_lshlrev_b32_e32 v100, 16, v195
	v_and_b32_e32 v101, 0xffff0000, v195
	v_pk_add_f32 v[94:95], v[94:95], v[100:101]
	v_pk_add_f32 v[98:99], v[92:93], v[98:99]
	v_cvt_pk_bf16_f32 v93, v94, v95
	v_cvt_pk_bf16_f32 v92, v98, v99
	v_mul_f32_e32 v99, v99, v99
	v_mul_f32_e32 v95, v95, v95
	v_fmac_f32_e32 v99, v98, v98
	v_fmac_f32_e32 v95, v94, v94
	v_add_f32_e32 v100, v99, v95
	v_lshlrev_b32_e32 v94, 16, v196
	v_and_b32_e32 v95, 0xffff0000, v196
	v_lshlrev_b32_e32 v98, 16, v197
	v_and_b32_e32 v99, 0xffff0000, v197
	v_pk_add_f32 v[88:89], v[88:89], v[94:95]
	v_pk_add_f32 v[90:91], v[90:91], v[98:99]
	v_cvt_pk_bf16_f32 v94, v88, v89
	v_mul_f32_e32 v89, v89, v89
	v_fmac_f32_e32 v89, v88, v88
	v_mul_f32_e32 v88, v91, v91
	v_fmac_f32_e32 v88, v90, v90
	v_add_f32_e32 v88, v89, v88
	v_add_f32_e32 v98, v100, v88
	v_lshl_add_u64 v[88:89], s[78:79], 0, v[168:169]
	v_lshl_add_u64 v[88:89], v[88:89], 0, s[18:19]
	v_lshl_add_u64 v[88:89], v[88:89], 0, s[0:1]
	v_cvt_pk_bf16_f32 v95, v90, v91
	v_lshl_add_u64 v[88:89], v[88:89], 0, v[148:149]
	v_lshlrev_b32_e32 v90, 16, v136
	v_and_b32_e32 v91, 0xffff0000, v136
	global_store_dwordx4 v[88:89], v[92:95], off
	v_pk_add_f32 v[90:91], v[84:85], v[90:91]
	v_mul_f32_e32 v113, v181, v181
	v_lshlrev_b32_e32 v92, 16, v137
	v_and_b32_e32 v93, 0xffff0000, v137
	v_pk_add_f32 v[86:87], v[86:87], v[92:93]
	v_mul_f32_e32 v85, v91, v91
	v_cvt_pk_bf16_f32 v84, v90, v91
	v_fmac_f32_e32 v85, v90, v90
	v_mul_f32_e32 v90, v87, v87
	v_fmac_f32_e32 v90, v86, v86
	v_add_f32_e32 v85, v85, v90
	v_lshlrev_b32_e32 v90, 16, v138
	v_and_b32_e32 v91, 0xffff0000, v138
	v_lshlrev_b32_e32 v92, 16, v139
	v_and_b32_e32 v93, 0xffff0000, v139
	v_pk_add_f32 v[82:83], v[82:83], v[92:93]
	v_pk_add_f32 v[80:81], v[80:81], v[90:91]
	v_mul_f32_e32 v91, v83, v83
	v_mul_f32_e32 v90, v81, v81
	v_fmac_f32_e32 v90, v80, v80
	v_fmac_f32_e32 v91, v82, v82
	v_add_f32_e32 v85, v98, v85
	v_add_f32_e32 v90, v90, v91
	v_add_f32_e32 v90, v90, v85
	v_cvt_pk_bf16_f32 v85, v86, v87
	v_cvt_pk_bf16_f32 v86, v80, v81
	v_cvt_pk_bf16_f32 v87, v82, v83
	global_store_dwordx4 v[88:89], v[84:87], off offset:256
	s_waitcnt vmcnt(8)
	v_lshlrev_b32_e32 v82, 16, v132
	v_and_b32_e32 v83, 0xffff0000, v132
	v_lshlrev_b32_e32 v84, 16, v133
	v_and_b32_e32 v85, 0xffff0000, v133
	v_pk_add_f32 v[78:79], v[78:79], v[84:85]
	v_pk_add_f32 v[82:83], v[76:77], v[82:83]
	v_cvt_pk_bf16_f32 v77, v78, v79
	v_cvt_pk_bf16_f32 v76, v82, v83
	v_mul_f32_e32 v83, v83, v83
	v_mul_f32_e32 v79, v79, v79
	v_fmac_f32_e32 v83, v82, v82
	v_fmac_f32_e32 v79, v78, v78
	v_add_f32_e32 v84, v83, v79
	v_lshlrev_b32_e32 v78, 16, v134
	v_and_b32_e32 v79, 0xffff0000, v134
	v_lshlrev_b32_e32 v82, 16, v135
	v_and_b32_e32 v83, 0xffff0000, v135
	v_pk_add_f32 v[72:73], v[72:73], v[78:79]
	v_pk_add_f32 v[74:75], v[74:75], v[82:83]
	v_cvt_pk_bf16_f32 v78, v72, v73
	v_mul_f32_e32 v73, v73, v73
	v_fmac_f32_e32 v73, v72, v72
	v_mul_f32_e32 v72, v75, v75
	v_cvt_pk_bf16_f32 v79, v74, v75
	v_fmac_f32_e32 v72, v74, v74
	v_lshlrev_b32_e32 v74, 16, v128
	v_and_b32_e32 v75, 0xffff0000, v128
	v_lshlrev_b32_e32 v82, 16, v129
	v_and_b32_e32 v83, 0xffff0000, v129
	v_pk_add_f32 v[70:71], v[70:71], v[82:83]
	v_pk_add_f32 v[68:69], v[68:69], v[74:75]
	v_mul_f32_e32 v75, v71, v71
	v_mul_f32_e32 v74, v69, v69
	v_add_f32_e32 v72, v73, v72
	v_fmac_f32_e32 v74, v68, v68
	v_fmac_f32_e32 v75, v70, v70
	v_add_f32_e32 v84, v84, v72
	v_add_f32_e32 v74, v74, v75
	v_add_f32_e32 v84, v84, v74
	v_lshlrev_b32_e32 v74, 16, v130
	v_and_b32_e32 v75, 0xffff0000, v130
	v_lshlrev_b32_e32 v82, 16, v131
	v_and_b32_e32 v83, 0xffff0000, v131
	v_pk_add_f32 v[82:83], v[66:67], v[82:83]
	v_pk_add_f32 v[74:75], v[64:65], v[74:75]
	v_mul_f32_e32 v65, v83, v83
	v_mul_f32_e32 v64, v75, v75
	v_fmac_f32_e32 v179, v182, v182
	v_fmac_f32_e32 v113, v180, v180
	v_fmac_f32_e32 v64, v74, v74
	v_fmac_f32_e32 v65, v82, v82
	v_add_f32_e32 v113, v179, v113
	v_add_f32_e32 v64, v64, v65
	v_add_f32_e32 v112, v113, v112
	v_add_f32_e32 v64, v64, v84
	ds_bpermute_b32 v113, v176, v112
	ds_bpermute_b32 v107, v176, v106
	ds_bpermute_b32 v91, v176, v90
	ds_bpermute_b32 v65, v176, v64
	v_lshl_add_u64 v[72:73], s[78:79], 0, v[166:167]
	s_waitcnt lgkmcnt(3)
	v_add_f32_e32 v112, v112, v113
	s_waitcnt lgkmcnt(2)
	v_add_f32_e32 v96, v106, v107
	s_waitcnt lgkmcnt(1)
	v_add_f32_e32 v80, v90, v91
	s_waitcnt lgkmcnt(0)
	v_add_f32_e32 v64, v64, v65
	ds_bpermute_b32 v113, v163, v112
	ds_bpermute_b32 v97, v163, v96
	ds_bpermute_b32 v81, v163, v80
	ds_bpermute_b32 v65, v163, v64
	v_lshl_add_u64 v[72:73], v[72:73], 0, s[18:19]
	v_lshl_add_u64 v[72:73], v[72:73], 0, s[0:1]
	v_lshl_add_u64 v[72:73], v[72:73], 0, v[148:149]
	global_store_dwordx4 v[72:73], v[76:79], off
	v_cvt_pk_bf16_f32 v66, v68, v69
	v_cvt_pk_bf16_f32 v67, v70, v71
	v_cvt_pk_bf16_f32 v68, v74, v75
	v_cvt_pk_bf16_f32 v69, v82, v83
	v_lshl_add_u64 v[76:77], s[20:21], 2, v[152:153]
	global_store_dwordx4 v[72:73], v[66:69], off offset:256
	s_waitcnt vmcnt(8)
	s_and_saveexec_b64 s[20:21], s[2:3]
	s_cbranch_execz .LBB0_1557
	s_waitcnt lgkmcnt(3)
	v_add_f32_e32 v67, v112, v113
	s_waitcnt lgkmcnt(0)
	v_add_f32_e32 v64, v64, v65
	v_add_f32_e32 v65, v80, v81
	v_add_f32_e32 v66, v96, v97
	global_atomic_add_f32 v[76:77], v67, off
	global_atomic_add_f32 v[76:77], v66, off offset:64
	global_atomic_add_f32 v[76:77], v65, off offset:128
	global_atomic_add_f32 v[76:77], v64, off offset:192

.LBB0_1719:
	s_mov_b32 s98, 0x40000
	s_mov_b32 s99, 0
	s_lshl_b32 s22, s53, 8
	s_lshl_b32 s20, s15, 8
	v_add_u32_e32 v140, s22, v225
	s_ashr_i32 s21, s20, 31
	s_lshl_b64 s[20:21], s[20:21], 1
	v_ashrrev_i32_e32 v141, 31, v140
	v_lshl_add_u64 v[142:143], v[204:205], 0, s[20:21]
	v_lshlrev_b64 v[128:129], 11, v[140:141]
	v_lshl_add_u64 v[130:131], v[142:143], 0, v[128:129]
	v_lshl_add_u64 v[190:191], v[130:131], 0, s[98:99]
	global_load_dwordx4 v[150:153], v[130:131], off
	global_load_dwordx4 v[154:157], v[130:131], off offset:256
	global_load_dwordx4 v[182:185], v[190:191], off
	global_load_dwordx4 v[186:189], v[190:191], off offset:256
	v_and_b32_e32 v131, 64, v230
	v_xor_b32_e32 v130, 16, v230
	v_add_u32_e32 v131, 64, v131
	v_cmp_lt_i32_e32 vcc, v130, v131
	v_xor_b32_e32 v132, 32, v230
	v_or_b32_e32 v134, 48, v140
	v_cndmask_b32_e32 v133, v230, v130, vcc
	v_or_b32_e32 v130, 16, v140
	v_cmp_lt_i32_e32 vcc, v132, v131
	v_ashrrev_i32_e32 v131, 31, v130
	v_lshlrev_b64 v[170:171], 11, v[130:131]
	v_lshl_add_u64 v[130:131], v[142:143], 0, v[170:171]
	v_lshl_add_u64 v[190:191], v[130:131], 0, s[98:99]
	global_load_dwordx4 v[158:161], v[130:131], off
	v_cndmask_b32_e32 v135, v230, v132, vcc
	v_or_b32_e32 v132, 32, v140
	v_lshlrev_b32_e32 v148, 2, v133
	v_ashrrev_i32_e32 v133, 31, v132
	v_lshlrev_b32_e32 v141, 2, v135
	v_ashrrev_i32_e32 v135, 31, v134
	v_lshlrev_b64 v[146:147], 11, v[132:133]
	v_lshlrev_b64 v[144:145], 11, v[134:135]
	v_lshl_add_u64 v[128:129], s[78:79], 0, v[128:129]
	v_lshl_add_u64 v[132:133], v[142:143], 0, v[146:147]
	v_lshl_add_u64 v[172:173], v[142:143], 0, v[144:145]
	v_lshl_add_u64 v[174:175], v[128:129], 0, s[20:21]
	global_load_dwordx4 v[162:165], v[130:131], off offset:256
	global_load_dwordx4 v[216:219], v[190:191], off
	global_load_dwordx4 v[220:223], v[190:191], off offset:256
	v_lshl_add_u64 v[190:191], v[132:133], 0, s[98:99]
	global_load_dwordx4 v[166:169], v[132:133], off
	global_load_dwordx4 v[136:139], v[132:133], off offset:256
	global_load_dwordx4 v[236:239], v[190:191], off
	global_load_dwordx4 v[240:243], v[190:191], off offset:256
	s_nop 0
	v_lshl_add_u64 v[190:191], v[172:173], 0, s[98:99]
	global_load_dwordx4 v[132:135], v[172:173], off
	global_load_dwordx4 v[128:131], v[172:173], off offset:256
	global_load_dwordx4 v[246:249], v[190:191], off
	global_load_dwordx4 v[250:253], v[190:191], off offset:256
	s_mov_b32 s15, s1
	v_lshl_add_u64 v[172:173], v[174:175], 0, s[14:15]
	v_lshl_add_u64 v[172:173], v[172:173], 0, v[200:201]
	s_ashr_i32 s23, s22, 31
	s_waitcnt vmcnt(14)
	v_lshlrev_b32_e32 v174, 16, v150
	v_and_b32_e32 v175, 0xffff0000, v150
	v_lshlrev_b32_e32 v150, 16, v151
	v_and_b32_e32 v151, 0xffff0000, v151
	v_lshlrev_b32_e32 v176, 16, v152
	v_and_b32_e32 v177, 0xffff0000, v152
	v_lshlrev_b32_e32 v152, 16, v153
	v_and_b32_e32 v153, 0xffff0000, v153
	v_lshlrev_b32_e32 v178, 16, v154
	v_and_b32_e32 v179, 0xffff0000, v154
	v_lshlrev_b32_e32 v154, 16, v155
	v_and_b32_e32 v155, 0xffff0000, v155
	v_lshlrev_b32_e32 v180, 16, v156
	v_and_b32_e32 v181, 0xffff0000, v156
	v_lshlrev_b32_e32 v156, 16, v157
	v_and_b32_e32 v157, 0xffff0000, v157
	v_pk_fma_f32 v[126:127], v[126:127], 0.5, v[150:151] op_sel_hi:[1,0,1]
	v_pk_fma_f32 v[124:125], v[124:125], 0.5, v[174:175] op_sel_hi:[1,0,1]
	v_pk_fma_f32 v[122:123], v[122:123], 0.5, v[152:153] op_sel_hi:[1,0,1]
	v_pk_fma_f32 v[120:121], v[120:121], 0.5, v[176:177] op_sel_hi:[1,0,1]
	v_pk_fma_f32 v[118:119], v[118:119], 0.5, v[154:155] op_sel_hi:[1,0,1]
	v_pk_fma_f32 v[150:151], v[116:117], 0.5, v[178:179] op_sel_hi:[1,0,1]
	v_pk_fma_f32 v[152:153], v[114:115], 0.5, v[156:157] op_sel_hi:[1,0,1]
	v_pk_fma_f32 v[154:155], v[112:113], 0.5, v[180:181] op_sel_hi:[1,0,1]
	v_cvt_pk_bf16_f32 v112, v124, v125
	v_mul_f32_e32 v117, v125, v125
	v_mul_f32_e32 v125, v127, v127
	v_cvt_pk_bf16_f32 v114, v120, v121
	v_cvt_pk_bf16_f32 v115, v122, v123
	v_mul_f32_e32 v121, v121, v121
	v_mul_f32_e32 v123, v123, v123
	v_cvt_pk_bf16_f32 v113, v126, v127
	v_mul_f32_e32 v127, v151, v151
	v_mul_f32_e32 v149, v119, v119
	v_fmac_f32_e32 v117, v124, v124
	v_fmac_f32_e32 v125, v126, v126
	v_fmac_f32_e32 v121, v120, v120
	v_fmac_f32_e32 v123, v122, v122
	global_store_dwordx4 v[172:173], v[112:115], off
	v_fmac_f32_e32 v127, v150, v150
	v_fmac_f32_e32 v149, v118, v118
	v_add_f32_e32 v112, v117, v125
	v_add_f32_e32 v113, v121, v123
	v_add_f32_e32 v114, v127, v149
	v_add_f32_e32 v112, v112, v113
	v_add_f32_e32 v112, v112, v114
	v_mul_f32_e32 v113, v155, v155
	v_mul_f32_e32 v114, v153, v153
	v_cvt_pk_bf16_f32 v116, v150, v151
	v_fmac_f32_e32 v113, v154, v154
	v_fmac_f32_e32 v114, v152, v152
	v_cvt_pk_bf16_f32 v117, v118, v119
	v_cvt_pk_bf16_f32 v118, v154, v155
	v_cvt_pk_bf16_f32 v119, v152, v153
	v_add_f32_e32 v113, v113, v114
	global_store_dwordx4 v[172:173], v[116:119], off offset:256
	s_waitcnt vmcnt(12)
	v_lshlrev_b32_e32 v114, 16, v158
	v_and_b32_e32 v115, 0xffff0000, v158
	v_lshlrev_b32_e32 v116, 16, v159
	v_and_b32_e32 v117, 0xffff0000, v159
	v_pk_fma_f32 v[110:111], v[110:111], 0.5, v[116:117] op_sel_hi:[1,0,1]
	v_pk_fma_f32 v[114:115], v[108:109], 0.5, v[114:115] op_sel_hi:[1,0,1]
	v_cvt_pk_bf16_f32 v109, v110, v111
	v_cvt_pk_bf16_f32 v108, v114, v115
	v_mul_f32_e32 v115, v115, v115
	v_mul_f32_e32 v111, v111, v111
	v_fmac_f32_e32 v115, v114, v114
	v_fmac_f32_e32 v111, v110, v110
	v_add_f32_e32 v116, v115, v111
	v_lshlrev_b32_e32 v110, 16, v160
	v_and_b32_e32 v111, 0xffff0000, v160
	v_lshlrev_b32_e32 v114, 16, v161
	v_and_b32_e32 v115, 0xffff0000, v161
	v_pk_fma_f32 v[104:105], v[104:105], 0.5, v[110:111] op_sel_hi:[1,0,1]
	v_pk_fma_f32 v[106:107], v[106:107], 0.5, v[114:115] op_sel_hi:[1,0,1]
	v_cvt_pk_bf16_f32 v110, v104, v105
	v_mul_f32_e32 v105, v105, v105
	v_fmac_f32_e32 v105, v104, v104
	v_mul_f32_e32 v104, v107, v107
	v_fmac_f32_e32 v104, v106, v106
	v_add_f32_e32 v104, v105, v104
	v_add_f32_e32 v114, v116, v104
	v_lshl_add_u64 v[104:105], s[78:79], 0, v[170:171]
	v_lshl_add_u64 v[104:105], v[104:105], 0, s[20:21]
	v_lshl_add_u64 v[104:105], v[104:105], 0, s[14:15]
	v_cvt_pk_bf16_f32 v111, v106, v107
	v_lshl_add_u64 v[104:105], v[104:105], 0, v[200:201]
	v_lshlrev_b32_e32 v106, 16, v162
	v_and_b32_e32 v107, 0xffff0000, v162
	global_store_dwordx4 v[104:105], v[108:111], off
	v_pk_fma_f32 v[106:107], v[100:101], 0.5, v[106:107] op_sel_hi:[1,0,1]
	v_add_f32_e32 v112, v113, v112
	v_lshlrev_b32_e32 v108, 16, v163
	v_and_b32_e32 v109, 0xffff0000, v163
	v_pk_fma_f32 v[102:103], v[102:103], 0.5, v[108:109] op_sel_hi:[1,0,1]
	v_mul_f32_e32 v101, v107, v107
	v_cvt_pk_bf16_f32 v100, v106, v107
	v_fmac_f32_e32 v101, v106, v106
	v_mul_f32_e32 v106, v103, v103
	v_fmac_f32_e32 v106, v102, v102
	v_add_f32_e32 v101, v101, v106
	v_lshlrev_b32_e32 v106, 16, v164
	v_and_b32_e32 v107, 0xffff0000, v164
	v_lshlrev_b32_e32 v108, 16, v165
	v_and_b32_e32 v109, 0xffff0000, v165
	v_pk_fma_f32 v[98:99], v[98:99], 0.5, v[108:109] op_sel_hi:[1,0,1]
	v_pk_fma_f32 v[96:97], v[96:97], 0.5, v[106:107] op_sel_hi:[1,0,1]
	v_mul_f32_e32 v107, v99, v99
	v_mul_f32_e32 v106, v97, v97
	v_fmac_f32_e32 v106, v96, v96
	v_fmac_f32_e32 v107, v98, v98
	v_add_f32_e32 v101, v114, v101
	v_add_f32_e32 v106, v106, v107
	v_add_f32_e32 v106, v106, v101
	v_cvt_pk_bf16_f32 v101, v102, v103
	v_cvt_pk_bf16_f32 v102, v96, v97
	v_cvt_pk_bf16_f32 v103, v98, v99
	global_store_dwordx4 v[104:105], v[100:103], off offset:256
	s_waitcnt vmcnt(10)
	v_lshlrev_b32_e32 v98, 16, v166
	v_and_b32_e32 v99, 0xffff0000, v166
	v_lshlrev_b32_e32 v100, 16, v167
	v_and_b32_e32 v101, 0xffff0000, v167
	v_pk_fma_f32 v[94:95], v[94:95], 0.5, v[100:101] op_sel_hi:[1,0,1]
	v_pk_fma_f32 v[98:99], v[92:93], 0.5, v[98:99] op_sel_hi:[1,0,1]
	v_cvt_pk_bf16_f32 v93, v94, v95
	v_cvt_pk_bf16_f32 v92, v98, v99
	v_mul_f32_e32 v99, v99, v99
	v_mul_f32_e32 v95, v95, v95
	v_fmac_f32_e32 v99, v98, v98
	v_fmac_f32_e32 v95, v94, v94
	v_add_f32_e32 v100, v99, v95
	v_lshlrev_b32_e32 v94, 16, v168
	v_and_b32_e32 v95, 0xffff0000, v168
	v_lshlrev_b32_e32 v98, 16, v169
	v_and_b32_e32 v99, 0xffff0000, v169
	v_pk_fma_f32 v[88:89], v[88:89], 0.5, v[94:95] op_sel_hi:[1,0,1]
	v_pk_fma_f32 v[90:91], v[90:91], 0.5, v[98:99] op_sel_hi:[1,0,1]
	v_cvt_pk_bf16_f32 v94, v88, v89
	v_mul_f32_e32 v89, v89, v89
	v_fmac_f32_e32 v89, v88, v88
	v_mul_f32_e32 v88, v91, v91
	v_fmac_f32_e32 v88, v90, v90
	v_add_f32_e32 v88, v89, v88
	v_add_f32_e32 v98, v100, v88
	v_lshl_add_u64 v[88:89], s[78:79], 0, v[146:147]
	v_lshl_add_u64 v[88:89], v[88:89], 0, s[20:21]
	v_lshl_add_u64 v[88:89], v[88:89], 0, s[14:15]
	v_cvt_pk_bf16_f32 v95, v90, v91
	v_lshl_add_u64 v[88:89], v[88:89], 0, v[200:201]
	v_lshlrev_b32_e32 v90, 16, v136
	v_and_b32_e32 v91, 0xffff0000, v136
	global_store_dwordx4 v[88:89], v[92:95], off
	v_pk_fma_f32 v[90:91], v[84:85], 0.5, v[90:91] op_sel_hi:[1,0,1]
	ds_bpermute_b32 v113, v148, v112
	v_lshlrev_b32_e32 v92, 16, v137
	v_and_b32_e32 v93, 0xffff0000, v137
	v_pk_fma_f32 v[86:87], v[86:87], 0.5, v[92:93] op_sel_hi:[1,0,1]
	v_mul_f32_e32 v85, v91, v91
	v_cvt_pk_bf16_f32 v84, v90, v91
	v_fmac_f32_e32 v85, v90, v90
	v_mul_f32_e32 v90, v87, v87
	v_fmac_f32_e32 v90, v86, v86
	v_add_f32_e32 v85, v85, v90
	v_lshlrev_b32_e32 v90, 16, v138
	v_and_b32_e32 v91, 0xffff0000, v138
	v_lshlrev_b32_e32 v92, 16, v139
	v_and_b32_e32 v93, 0xffff0000, v139
	v_pk_fma_f32 v[82:83], v[82:83], 0.5, v[92:93] op_sel_hi:[1,0,1]
	v_pk_fma_f32 v[80:81], v[80:81], 0.5, v[90:91] op_sel_hi:[1,0,1]
	v_mul_f32_e32 v91, v83, v83
	v_mul_f32_e32 v90, v81, v81
	v_fmac_f32_e32 v90, v80, v80
	v_fmac_f32_e32 v91, v82, v82
	v_add_f32_e32 v85, v98, v85
	v_add_f32_e32 v90, v90, v91
	v_add_f32_e32 v90, v90, v85
	v_cvt_pk_bf16_f32 v85, v86, v87
	v_cvt_pk_bf16_f32 v86, v80, v81
	v_cvt_pk_bf16_f32 v87, v82, v83
	global_store_dwordx4 v[88:89], v[84:87], off offset:256
	s_waitcnt vmcnt(8)
	v_lshlrev_b32_e32 v82, 16, v132
	v_and_b32_e32 v83, 0xffff0000, v132
	v_lshlrev_b32_e32 v84, 16, v133
	v_and_b32_e32 v85, 0xffff0000, v133
	v_pk_fma_f32 v[78:79], v[78:79], 0.5, v[84:85] op_sel_hi:[1,0,1]
	v_pk_fma_f32 v[82:83], v[76:77], 0.5, v[82:83] op_sel_hi:[1,0,1]
	v_cvt_pk_bf16_f32 v77, v78, v79
	v_cvt_pk_bf16_f32 v76, v82, v83
	v_mul_f32_e32 v83, v83, v83
	v_mul_f32_e32 v79, v79, v79
	v_fmac_f32_e32 v83, v82, v82
	v_fmac_f32_e32 v79, v78, v78
	v_add_f32_e32 v84, v83, v79
	v_lshlrev_b32_e32 v78, 16, v134
	v_and_b32_e32 v79, 0xffff0000, v134
	v_lshlrev_b32_e32 v82, 16, v135
	v_and_b32_e32 v83, 0xffff0000, v135
	v_pk_fma_f32 v[72:73], v[72:73], 0.5, v[78:79] op_sel_hi:[1,0,1]
	v_pk_fma_f32 v[74:75], v[74:75], 0.5, v[82:83] op_sel_hi:[1,0,1]
	v_cvt_pk_bf16_f32 v78, v72, v73
	v_mul_f32_e32 v73, v73, v73
	v_fmac_f32_e32 v73, v72, v72
	v_mul_f32_e32 v72, v75, v75
	v_cvt_pk_bf16_f32 v79, v74, v75
	v_fmac_f32_e32 v72, v74, v74
	v_lshlrev_b32_e32 v74, 16, v128
	v_and_b32_e32 v75, 0xffff0000, v128
	v_lshlrev_b32_e32 v82, 16, v129
	v_and_b32_e32 v83, 0xffff0000, v129
	v_pk_fma_f32 v[70:71], v[70:71], 0.5, v[82:83] op_sel_hi:[1,0,1]
	v_pk_fma_f32 v[68:69], v[68:69], 0.5, v[74:75] op_sel_hi:[1,0,1]
	v_mul_f32_e32 v75, v71, v71
	v_mul_f32_e32 v74, v69, v69
	v_add_f32_e32 v72, v73, v72
	v_fmac_f32_e32 v74, v68, v68
	v_fmac_f32_e32 v75, v70, v70
	v_add_f32_e32 v84, v84, v72
	v_add_f32_e32 v74, v74, v75
	v_add_f32_e32 v84, v84, v74
	v_lshlrev_b32_e32 v74, 16, v130
	v_and_b32_e32 v75, 0xffff0000, v130
	v_lshlrev_b32_e32 v82, 16, v131
	v_and_b32_e32 v83, 0xffff0000, v131
	v_pk_fma_f32 v[82:83], v[66:67], 0.5, v[82:83] op_sel_hi:[1,0,1]
	v_pk_fma_f32 v[74:75], v[64:65], 0.5, v[74:75] op_sel_hi:[1,0,1]
	v_mul_f32_e32 v65, v83, v83
	v_mul_f32_e32 v64, v75, v75
	v_fmac_f32_e32 v64, v74, v74
	v_fmac_f32_e32 v65, v82, v82
	v_add_f32_e32 v64, v64, v65
	v_add_f32_e32 v64, v64, v84
	ds_bpermute_b32 v107, v148, v106
	ds_bpermute_b32 v91, v148, v90
	ds_bpermute_b32 v65, v148, v64
	s_waitcnt lgkmcnt(3)
	v_add_f32_e32 v112, v112, v113
	ds_bpermute_b32 v113, v141, v112
	s_waitcnt lgkmcnt(3)
	v_add_f32_e32 v96, v106, v107
	s_waitcnt lgkmcnt(2)
	v_add_f32_e32 v80, v90, v91
	s_waitcnt lgkmcnt(1)
	v_add_f32_e32 v64, v64, v65
	ds_bpermute_b32 v97, v141, v96
	ds_bpermute_b32 v81, v141, v80
	v_lshl_add_u64 v[72:73], s[78:79], 0, v[144:145]
	ds_bpermute_b32 v65, v141, v64
	v_lshl_add_u64 v[72:73], v[72:73], 0, s[20:21]
	v_lshl_add_u64 v[72:73], v[72:73], 0, s[14:15]
	v_lshl_add_u64 v[72:73], v[72:73], 0, v[200:201]
	global_store_dwordx4 v[72:73], v[76:79], off
	v_cvt_pk_bf16_f32 v66, v68, v69
	v_cvt_pk_bf16_f32 v67, v70, v71
	v_cvt_pk_bf16_f32 v68, v74, v75
	v_cvt_pk_bf16_f32 v69, v82, v83
	v_lshl_add_u64 v[76:77], s[22:23], 2, v[206:207]
	global_store_dwordx4 v[72:73], v[66:69], off offset:256
	s_waitcnt vmcnt(8)
	s_and_saveexec_b64 s[22:23], s[2:3]
	s_cbranch_execz .LBB0_1721
	s_waitcnt lgkmcnt(3)
	v_add_f32_e32 v67, v112, v113
	s_waitcnt lgkmcnt(0)
	v_add_f32_e32 v64, v64, v65
	v_add_f32_e32 v65, v80, v81
	v_add_f32_e32 v66, v96, v97
	global_atomic_add_f32 v[76:77], v67, off
	global_atomic_add_f32 v[76:77], v66, off offset:64
	global_atomic_add_f32 v[76:77], v65, off offset:128
	global_atomic_add_f32 v[76:77], v64, off offset:192
